# attention and retention-KV items rebalanced across workgroups (two windowed-attention items per workgroup on half the grid)
# speedup vs baseline: 1.0929x; 1.0067x over previous
.LBB0_751:
	s_or_b64 exec, exec, s[4:5]
	v_readlane_b32 s4, v245, 50
	v_readlane_b32 s5, v245, 51
	s_xor_b64 s[4:5], s[4:5], -1
	v_writelane_b32 v245, s4, 56
	v_mov_b32_e32 v96, v187
	s_nop 0
	v_writelane_b32 v245, s5, 57
	v_readlane_b32 s4, v246, 57
	v_readlane_b32 s5, v246, 58
	s_andn2_b64 vcc, exec, s[4:5]
	s_barrier
	v_writelane_b32 v245, s85, 58
	s_cbranch_vccnz .LBB0_917
	s_lshl_b32 s0, s85, 3
	v_writelane_b32 v245, s0, 59
	s_movk_i32 s0, 0x1d1
	v_cmp_gt_i32_e64 s[4:5], s0, v96
	v_max_i32_e32 v0, 0xd1, v96
	v_sub_u32_e32 v0, v0, v96
	v_writelane_b32 v245, s4, 60
	s_lshl_b32 s0, s85, 2
	v_add_u32_e32 v0, 0xff, v0
	v_writelane_b32 v245, s5, 61
	v_writelane_b32 v245, s0, 62
	v_lshrrev_b32_e32 v2, 8, v0
	s_movk_i32 s0, 0xff
	v_add_u32_e32 v2, 1, v2
	v_cmp_lt_u32_e64 s[4:5], s0, v0
	s_waitcnt vmcnt(32)
	v_and_b32_e32 v160, 0x1fffffe, v2
	v_lshlrev_b32_e32 v162, 2, v96
	v_writelane_b32 v245, s4, 63
	v_readlane_b32 s54, v247, 0
	v_readlane_b32 s0, v245, 39
	v_writelane_b32 v244, s5, 0
	v_cmp_ne_u32_e64 s[4:5], v2, v160
	v_lshl_add_u32 v161, v160, 8, v96
	v_add_u32_e32 v97, 0x100, v96
	v_writelane_b32 v244, s4, 1
	v_add_u32_e32 v163, s0, v162
	s_mov_b32 s52, s54
	v_writelane_b32 v244, s5, 2
	v_readlane_b32 s53, v245, 36
	v_readlane_b32 s13, v245, 34
	v_readlane_b32 s0, v245, 30
	s_nop 1
	v_writelane_b32 v244, s0, 3
	s_mov_b32 s98, 0
	s_branch .Lp2_item

.LBB0_754:
	s_add_i32 s98, s98, 1
	s_cmp_lt_u32 s98, 3
	s_cbranch_scc0 .LBB0_916
.Lp2_item:
	v_readlane_b32 s54, v247, 0
	s_lshl_b32 s99, s98, 8
	s_cmp_eq_u32 s98, 2
	s_cselect_b32 s32, 0x100, 0
	s_add_i32 s99, s99, s32
	s_cmp_lt_u32 s54, 0x100
	s_cbranch_scc1 .Lp2_lo
	s_addk_i32 s99, 0x100
	s_cmp_eq_u32 s98, 1
	s_cselect_b32 s32, 0x100, 0
	s_add_i32 s99, s99, s32
.Lp2_lo:
	s_add_i32 s54, s54, s99
	s_mov_b32 s52, s54
	s_add_i32 s53, s54, 0xfffffe00
	s_lshl_b32 s13, s54, 4
	s_lshl_b32 s32, s54, 5
	v_writelane_b32 v244, s32, 3
